# SwiGLU epilogue restructured (hoisted ps loads, batched shuffles, interleaved silu chains) + MLA r2b loop rescheduled
# speedup vs baseline: 1.0260x; 1.0260x over previous
; #define ALAS __attribute__((address_space(3)))
; template <bool SUB> __device__ __forceinline__ void attn_unit_r2b(const AU& u, ALAS unsigned char* lds, float mb2) {
;     ...
;     const int kr0 = tid / 12, kc0 = tid - kr0 * 12, c1 = tid + 512, kr1 = c1 / 12, kc1 = c1 - kr1 * 12, vr_ = tid >> 3, vc_ = tid & 7;
;     const bool k2 = tid < 256;
;     const bf16_t* kg0 = u.K + (size_t)kr0 * u.krs + kc0 * 8; const bf16_t* kg1 = u.K + (size_t)kr1 * u.krs + kc1 * 8; const bf16_t* vg = u.V + (size_t)vr_ * u.vrs + vc_ * 8;
;     const int kl0 = kr0 * KP + kc0 * 16, kl1 = kr1 * KP + kc1 * 16, vl = V_OFF + vr_ * VP + vc_ * 16;
;     f32x16 oa0, oa1, ob0, ob1;
; #pragma unroll
;     for (int i = 0; i < 16; ++i) { oa0[i] = 0.f; oa1[i] = 0.f; ob0[i] = 0.f; ob1[i] = 0.f; }
;     float la = 0.f, lb = 0.f;
;     u32x4 rk0 = *(const u32x4*)kg0, rk1 = (u32x4){0u, 0u, 0u, 0u}, rv = *(const u32x4*)vg;
;     if (k2) rk1 = *(const u32x4*)kg1;
;     *(ALAS u32x4*)(lds + kl0) = rk0; if (k2) *(ALAS u32x4*)(lds + kl1) = rk1; *(ALAS u32x4*)(lds + vl) = rv;
;     __syncthreads();
;     for (int t = 0; t < NT; ++t) {
;         const int cur = t & 1;
;         if (t + 1 < NT) { const size_t ro = (size_t)(t + 1) * 64; rk0 = *(const u32x4*)(kg0 + ro * u.krs); if (k2) rk1 = *(const u32x4*)(kg1 + ro * u.krs); rv = *(const u32x4*)(vg + ro * u.vrs); }
.LBB0_277:
	s_or_b64 exec, exec, s[56:57]
	s_movk_i32 s34, 0xc00
	v_mad_i64_i32 v[6:7], s[56:57], v19, s34, 0
	s_movk_i32 s34, 0x90
	v_mul_lo_u32 v8, v12, s34
	v_add3_u32 v196, 0, v8, v14
	v_mul_u32_u24_e32 v8, 0xd0, v18
	v_add3_u32 v168, 0, v8, v168
	v_bfe_u32 v8, v0, 2, 2
	v_lshl_or_b32 v1, v1, 2, v8
	v_lshlrev_b32_e32 v8, 1, v0
	v_lshlrev_b32_e32 v0, 3, v0
	v_mad_u32_u24 v1, v1, s34, 0
	v_and_b32_e32 v8, 32, v8
	v_and_b32_e32 v0, 24, v0
	v_readlane_b32 s34, v254, 45
	v_add3_u32 v197, v1, v8, v0
	v_lshl_add_u64 v[0:1], s[42:43], 0, v[16:17]
	v_mov_b32_e32 v15, v169
	s_add_u32 s56, s34, s44
	v_readlane_b32 s34, v254, 46
	v_lshl_add_u64 v[0:1], v[0:1], 0, v[14:15]
	s_addc_u32 s57, s34, s45
	v_lshl_add_u64 v[166:167], s[56:57], 0, v[0:1]
	s_add_u32 s56, s22, s7
	s_addc_u32 s57, s23, s2
	v_lshl_add_u64 v[0:1], s[56:57], 0, v[6:7]
	v_readlane_b32 s34, v254, 47
	v_lshl_add_u64 v[0:1], v[4:5], 1, v[0:1]
	v_readlane_b32 s35, v254, 48
	v_mov_b32_e32 v32, 0
	s_mov_b32 s62, 0
	v_lshl_add_u64 v[172:173], s[34:35], 0, v[0:1]
	v_lshl_add_u64 v[0:1], s[56:57], 0, v[10:11]
	v_lshl_add_u64 v[0:1], v[2:3], 1, v[0:1]
	v_lshl_add_u64 v[174:175], s[34:35], 0, v[0:1]
	v_mov_b32_e32 v33, v32
	v_mov_b32_e32 v34, v32
	v_mov_b32_e32 v35, v32
	v_mov_b32_e32 v36, v32
	v_mov_b32_e32 v37, v32
	v_mov_b32_e32 v38, v32
	v_mov_b32_e32 v39, v32
	v_mov_b32_e32 v40, v32
	v_mov_b32_e32 v41, v32
	v_mov_b32_e32 v42, v32
	v_mov_b32_e32 v43, v32
	v_mov_b32_e32 v44, v32
	v_mov_b32_e32 v45, v32
	v_mov_b32_e32 v46, v32
	v_mov_b32_e32 v47, v32
	v_mov_b32_e32 v48, v32
	v_mov_b32_e32 v49, v32
	v_mov_b32_e32 v50, v32
	v_mov_b32_e32 v51, v32
	v_mov_b32_e32 v52, v32
	v_mov_b32_e32 v53, v32
	v_mov_b32_e32 v54, v32
	v_mov_b32_e32 v55, v32
	v_mov_b32_e32 v56, v32
	v_mov_b32_e32 v57, v32
	v_mov_b32_e32 v58, v32
	v_mov_b32_e32 v59, v32
	v_mov_b32_e32 v60, v32
	v_mov_b32_e32 v61, v32
	v_mov_b32_e32 v62, v32
	v_mov_b32_e32 v63, v32
	v_mov_b32_e32 v0, v32
	v_mov_b32_e32 v1, v32
	v_mov_b32_e32 v2, v32
	v_mov_b32_e32 v3, v32
	v_mov_b32_e32 v4, v32
	v_mov_b32_e32 v5, v32
	v_mov_b32_e32 v6, v32
	v_mov_b32_e32 v7, v32
	v_mov_b32_e32 v8, v32
	v_mov_b32_e32 v9, v32
	v_mov_b32_e32 v10, v32
	v_mov_b32_e32 v11, v32
	v_mov_b32_e32 v12, v32
	v_mov_b32_e32 v13, v32
	v_mov_b32_e32 v14, v32
	v_mov_b32_e32 v15, v32
	v_mov_b32_e32 v16, v32
	v_mov_b32_e32 v17, v32
	v_mov_b32_e32 v18, v32
	v_mov_b32_e32 v19, v32
	v_mov_b32_e32 v20, v32
	v_mov_b32_e32 v21, v32
	v_mov_b32_e32 v22, v32
	v_mov_b32_e32 v23, v32
	v_mov_b32_e32 v24, v32
	v_mov_b32_e32 v25, v32
	v_mov_b32_e32 v26, v32
	v_mov_b32_e32 v27, v32
	v_mov_b32_e32 v28, v32
	v_mov_b32_e32 v29, v32
	v_mov_b32_e32 v30, v32
	v_mov_b32_e32 v31, v32
	v_mov_b32_e32 v164, v32
	v_mov_b32_e32 v165, v32
	s_waitcnt vmcnt(0)
	ds_write_b128 v196, v[160:163] offset:26624
	v_mov_b32_e32 v242, v32
	v_mov_b32_e32 v243, v32
	v_mov_b32_e32 v112, v32
	v_mov_b32_e32 v113, v32
	v_mov_b32_e32 v114, v32
	v_mov_b32_e32 v115, v32
	v_mov_b32_e32 v116, v32
	v_mov_b32_e32 v117, v32
	v_mov_b32_e32 v118, v32
	v_mov_b32_e32 v119, v32
	v_mov_b32_e32 v120, v32
	v_mov_b32_e32 v121, v32
	v_mov_b32_e32 v122, v32
	v_mov_b32_e32 v123, v32
	v_mov_b32_e32 v124, v32
	v_mov_b32_e32 v125, v32
	v_mov_b32_e32 v126, v32
	v_mov_b32_e32 v127, v32
	v_mov_b32_e32 v80, v32
	v_mov_b32_e32 v81, v32
	v_mov_b32_e32 v82, v32
	v_mov_b32_e32 v83, v32
	v_mov_b32_e32 v84, v32
	v_mov_b32_e32 v85, v32
	v_mov_b32_e32 v86, v32
	v_mov_b32_e32 v87, v32
	v_mov_b32_e32 v88, v32
	v_mov_b32_e32 v89, v32
	v_mov_b32_e32 v90, v32
	v_mov_b32_e32 v91, v32
	v_mov_b32_e32 v92, v32
	v_mov_b32_e32 v93, v32
	v_mov_b32_e32 v94, v32
	v_mov_b32_e32 v95, v32
	s_waitcnt lgkmcnt(0)
	s_barrier
	s_branch .Lr2b_top
.Lr2b_top:
	s_add_i32 s61, s62, 1
	s_cmp_lt_u32 s61, s28
	s_cselect_b64 s[56:57], -1, 0
	s_cbranch_scc0 .Lr2b_noload
	global_load_dwordx4 v[152:155], v[172:173], off
	s_and_saveexec_b64 s[58:59], s[40:41]
	s_cbranch_execz .Lr2b_nok2
	global_load_dwordx4 v[156:159], v[174:175], off

; #define ALAS __attribute__((address_space(3)))
; #define AMFMA(a, b, c) __builtin_amdgcn_mfma_f32_32x32x16_bf16((a), (b), (c), 0, 0, 0)
; template <bool SUB> __device__ __forceinline__ void attn_unit_r2b(const AU& u, ALAS unsigned char* lds, float mb2) {
;     ...
;         {
;             const ALAS unsigned char* kb = lds + cur * KBUF + r * KP + h * 16;
;             const ALAS unsigned char* vb = lds + V_OFF + cur * VBUF + (4 * h + ((lane & 15) >> 2)) * VP + ((lane >> 4) & 1) * 32 + (lane & 3) * 8;
;             bf16x8 paa[4], pab[4];
;             f32x16 Sa0, Sa1, Sb0, Sb1;
; #pragma unroll
;             for (int i = 0; i < 16; ++i) { Sa0[i] = 0.f; Sa1[i] = 0.f; Sb0[i] = 0.f; Sb1[i] = 0.f; }
; #pragma unroll
;             for (int d0 = 0; d0 < 6; ++d0) {
;                 const bf16x8 k0 = *(const ALAS bf16x8*)(kb + d0 * 32), k1 = *(const ALAS bf16x8*)(kb + 32 * KP + d0 * 32); const bf16x8 qbv = *(const ALAS bf16x8*)(qbl + d0 * 1024);
;                 Sa0 = AMFMA(k0, qa[d0], Sa0); Sa1 = AMFMA(k1, qa[d0], Sa1); Sb0 = AMFMA(k0, qbv, Sb0); Sb1 = AMFMA(k1, qbv, Sb1);
;                 if (d0 & 1) __builtin_amdgcn_sched_barrier(0);
;             }
;     ...
;             R2B_SOFT(Sa0, Sa1, paa, la);
;             __builtin_amdgcn_sched_barrier(0);
;             R2B_SOFT(Sb0, Sb1, pab, lb);
.Lr2b_noload:
	s_and_b32 s58, s62, 1
	s_mul_i32 s34, s58, 0x3400
	v_add_u32_e32 v188, s34, v168
	ds_read_b128 v[218:221], v188 offset:0
	ds_read_b128 v[222:225], v188 offset:32
	ds_read_b128 v[226:229], v188 offset:64
	ds_read_b128 v[230:233], v188 offset:96
	ds_read_b128 v[234:237], v188 offset:128
	ds_read_b128 v[238:241], v188 offset:160
	ds_read_b128 v[176:179], v193 offset:45056
	ds_read_b128 v[180:183], v193 offset:46080
	s_mul_i32 s34, s58, 0x2400
	v_add_u32_e32 v189, s34, v197
	s_waitcnt lgkmcnt(7)
	v_mfma_f32_32x32x16_bf16 v[96:111], v[218:221], v[128:131], 0
	v_lshl_add_u64 v[166:167], v[166:167], 0, s[8:9]
	v_add_f32_e32 v242, v112, v242
	v_add_f32_e32 v243, v80, v243
	v_add_f32_e32 v242, v113, v242
	v_add_f32_e32 v243, v81, v243
	s_waitcnt lgkmcnt(6)
	v_mfma_f32_32x32x16_bf16 v[96:111], v[222:225], v[132:135], v[96:111]
	v_lshl_add_u64 v[172:173], v[172:173], 0, s[12:13]
	v_add_f32_e32 v242, v114, v242
	v_add_f32_e32 v243, v82, v243
	v_add_f32_e32 v242, v115, v242
	v_add_f32_e32 v243, v83, v243
	s_waitcnt lgkmcnt(5)
	v_mfma_f32_32x32x16_bf16 v[96:111], v[226:229], v[136:139], v[96:111]
	v_lshl_add_u64 v[174:175], v[174:175], 0, s[12:13]
	v_add_f32_e32 v242, v116, v242
	v_add_f32_e32 v243, v84, v243
	v_add_f32_e32 v242, v117, v242
	v_add_f32_e32 v243, v85, v243
	s_waitcnt lgkmcnt(4)
	v_mfma_f32_32x32x16_bf16 v[96:111], v[230:233], v[140:143], v[96:111]
	v_add_f32_e32 v242, v118, v242
	v_add_f32_e32 v243, v86, v243
	v_add_f32_e32 v242, v119, v242
	v_add_f32_e32 v243, v87, v243
	v_add_f32_e32 v242, v120, v242
	s_waitcnt lgkmcnt(3)
	v_mfma_f32_32x32x16_bf16 v[96:111], v[234:237], v[144:147], v[96:111]
	v_add_f32_e32 v243, v88, v243
	v_add_f32_e32 v242, v121, v242
	v_add_f32_e32 v243, v89, v243
	v_add_f32_e32 v242, v122, v242
	v_add_f32_e32 v243, v90, v243
	v_add_f32_e32 v242, v123, v242
	s_waitcnt lgkmcnt(2)
	v_mfma_f32_32x32x16_bf16 v[96:111], v[238:241], v[148:151], v[96:111]
	v_add_f32_e32 v243, v91, v243
	v_add_f32_e32 v242, v124, v242
	v_add_f32_e32 v243, v92, v243
	v_add_f32_e32 v242, v125, v242
	v_add_f32_e32 v243, v93, v243
	v_add_f32_e32 v242, v126, v242
	s_waitcnt lgkmcnt(1)
	v_mfma_f32_32x32x16_bf16 v[64:79], v[218:221], v[176:179], 0
	ds_read_b128 v[176:179], v193 offset:47104
	ds_read_b128 v[218:221], v188 offset:6656
	v_add_f32_e32 v243, v94, v243
	v_add_f32_e32 v242, v127, v242
	v_add_f32_e32 v243, v95, v243
	s_waitcnt lgkmcnt(2)
	v_mfma_f32_32x32x16_bf16 v[64:79], v[222:225], v[180:183], v[64:79]
	ds_read_b128 v[180:183], v193 offset:48128
	ds_read_b128 v[222:225], v188 offset:6688
	v_exp_f32_e32 v96, v96
	v_exp_f32_e32 v97, v97
	s_waitcnt lgkmcnt(3)
	v_mfma_f32_32x32x16_bf16 v[64:79], v[226:229], v[176:179], v[64:79]
	ds_read_b128 v[176:179], v193 offset:49152
	ds_read_b128 v[226:229], v188 offset:6720
	v_exp_f32_e32 v98, v98
	v_exp_f32_e32 v99, v99
	s_waitcnt lgkmcnt(3)
	v_mfma_f32_32x32x16_bf16 v[64:79], v[230:233], v[180:183], v[64:79]
	ds_read_b128 v[180:183], v193 offset:50176
	ds_read_b128 v[230:233], v188 offset:6752
	v_exp_f32_e32 v100, v100
	v_exp_f32_e32 v101, v101
	s_waitcnt lgkmcnt(3)
	v_mfma_f32_32x32x16_bf16 v[64:79], v[234:237], v[176:179], v[64:79]
	ds_read_b128 v[234:237], v188 offset:6784
	ds_read_b128 v[176:179], v193 offset:45056
	v_exp_f32_e32 v102, v102
	v_exp_f32_e32 v103, v103
	s_waitcnt lgkmcnt(3)
	v_mfma_f32_32x32x16_bf16 v[64:79], v[238:241], v[180:183], v[64:79]
	ds_read_b128 v[238:241], v188 offset:6816
	ds_read_b128 v[180:183], v193 offset:46080
	v_exp_f32_e32 v104, v104
	v_exp_f32_e32 v105, v105
	v_exp_f32_e32 v106, v106
	v_exp_f32_e32 v107, v107
	v_mfma_f32_32x32x16_bf16 v[112:127], v[218:221], v[128:131], 0
	v_exp_f32_e32 v108, v108
	v_exp_f32_e32 v109, v109
	v_exp_f32_e32 v110, v110
	v_exp_f32_e32 v111, v111
	v_mfma_f32_32x32x16_bf16 v[112:127], v[222:225], v[132:135], v[112:127]
	v_exp_f32_e32 v64, v64
	v_exp_f32_e32 v65, v65
	v_exp_f32_e32 v66, v66
	v_mfma_f32_32x32x16_bf16 v[112:127], v[226:229], v[136:139], v[112:127]
	v_exp_f32_e32 v67, v67
	v_exp_f32_e32 v68, v68
	v_exp_f32_e32 v69, v69
	s_waitcnt lgkmcnt(4)
	v_mfma_f32_32x32x16_bf16 v[112:127], v[230:233], v[140:143], v[112:127]
	v_exp_f32_e32 v70, v70
	v_exp_f32_e32 v71, v71
	v_exp_f32_e32 v72, v72
	s_waitcnt lgkmcnt(3)
	v_mfma_f32_32x32x16_bf16 v[112:127], v[234:237], v[144:147], v[112:127]
	v_exp_f32_e32 v73, v73
	v_exp_f32_e32 v74, v74
	v_exp_f32_e32 v75, v75
	s_waitcnt lgkmcnt(1)
	v_mfma_f32_32x32x16_bf16 v[112:127], v[238:241], v[148:151], v[112:127]
	v_exp_f32_e32 v76, v76
	v_exp_f32_e32 v77, v77
	v_exp_f32_e32 v78, v78
	v_exp_f32_e32 v79, v79
	v_mfma_f32_32x32x16_bf16 v[80:95], v[218:221], v[176:179], 0
	ds_read_b128 v[176:179], v193 offset:47104
	v_cvt_pk_bf16_f32 v218, v96, v97
	v_cvt_pk_bf16_f32 v219, v98, v99
	v_cvt_pk_bf16_f32 v220, v100, v101
	v_cvt_pk_bf16_f32 v221, v102, v103
	s_waitcnt lgkmcnt(1)
	v_mfma_f32_32x32x16_bf16 v[80:95], v[222:225], v[180:183], v[80:95]
	ds_read_b128 v[180:183], v193 offset:48128
	v_cvt_pk_bf16_f32 v222, v64, v65
	v_cvt_pk_bf16_f32 v223, v66, v67
	v_cvt_pk_bf16_f32 v224, v68, v69
	v_cvt_pk_bf16_f32 v225, v70, v71
	v_exp_f32_e32 v112, v112
	v_exp_f32_e32 v113, v113
	s_waitcnt lgkmcnt(1)
	v_mfma_f32_32x32x16_bf16 v[80:95], v[226:229], v[176:179], v[80:95]
	ds_read_b128 v[176:179], v193 offset:49152
	v_cvt_pk_bf16_f32 v226, v104, v105
	v_cvt_pk_bf16_f32 v227, v106, v107
	v_cvt_pk_bf16_f32 v228, v108, v109
	v_cvt_pk_bf16_f32 v229, v110, v111
	v_exp_f32_e32 v114, v114
	v_exp_f32_e32 v115, v115
	s_waitcnt lgkmcnt(1)
; #define ALAS __attribute__((address_space(3)))
; __device__ __forceinline__ s16x4 vtr(const ALAS unsigned char* p) { return __builtin_bit_cast(s16x4, __builtin_amdgcn_ds_read_tr16_b64_v4i16((ALAS s16x4*)p)); }
; #define AMFMA(a, b, c) __builtin_amdgcn_mfma_f32_32x32x16_bf16((a), (b), (c), 0, 0, 0)
; template <bool SUB> __device__ __forceinline__ void attn_unit_r2b(const AU& u, ALAS unsigned char* lds, float mb2) {
;     ...
;             for (int ks = 0; ks < 4; ++ks) {
;                 const s16x4 lo0 = vtr(vb + ks * 16 * VP), hi0 = vtr(vb + (ks * 16 + 8) * VP), lo1 = vtr(vb + ks * 16 * VP + 64), hi1 = vtr(vb + (ks * 16 + 8) * VP + 64);
;                 const bf16x8 vf0 = __builtin_shufflevector(lo0, hi0, 0, 1, 2, 3, 4, 5, 6, 7), vf1 = __builtin_shufflevector(lo1, hi1, 0, 1, 2, 3, 4, 5, 6, 7);
;                 oa0 = AMFMA(paa[ks], vf0, oa0); oa1 = AMFMA(paa[ks], vf1, oa1); ob0 = AMFMA(pab[ks], vf0, ob0); ob1 = AMFMA(pab[ks], vf1, ob1);
;             }
;         }
;         if (t + 1 < NT) { *(ALAS u32x4*)(lds + (cur ^ 1) * KBUF + kl0) = rk0; if (k2) *(ALAS u32x4*)(lds + (cur ^ 1) * KBUF + kl1) = rk1; *(ALAS u32x4*)(lds + (cur ^ 1) * VBUF + vl) = rv; }
;         __syncthreads();
;     ...
;     la += __shfl_xor(la, 32); lb += __shfl_xor(lb, 32);
	v_mfma_f32_32x32x16_bf16 v[80:95], v[230:233], v[180:183], v[80:95]
	ds_read_b128 v[180:183], v193 offset:50176
	v_cvt_pk_bf16_f32 v230, v72, v73
	v_cvt_pk_bf16_f32 v231, v74, v75
	v_cvt_pk_bf16_f32 v232, v76, v77
	v_cvt_pk_bf16_f32 v233, v78, v79
	v_exp_f32_e32 v116, v116
	v_exp_f32_e32 v117, v117
	ds_read_b64_tr_b16 v[184:185], v189 offset:26624
	ds_read_b64_tr_b16 v[186:187], v189 offset:27776
	ds_read_b64_tr_b16 v[248:249], v189 offset:26688
	ds_read_b64_tr_b16 v[250:251], v189 offset:27840
	s_waitcnt lgkmcnt(5)
	v_mfma_f32_32x32x16_bf16 v[80:95], v[234:237], v[176:179], v[80:95]
	v_exp_f32_e32 v118, v118
	v_exp_f32_e32 v119, v119
	v_exp_f32_e32 v120, v120
	v_exp_f32_e32 v121, v121
	ds_read_b64_tr_b16 v[244:245], v189 offset:28928
	ds_read_b64_tr_b16 v[246:247], v189 offset:30080
	s_waitcnt lgkmcnt(6)
	v_mfma_f32_32x32x16_bf16 v[80:95], v[238:241], v[180:183], v[80:95]
	v_exp_f32_e32 v122, v122
	v_exp_f32_e32 v123, v123
	v_exp_f32_e32 v124, v124
	v_exp_f32_e32 v125, v125
	s_waitcnt lgkmcnt(4)
	v_mfma_f32_32x32x16_bf16 v[32:47], v[218:221], v[184:187], v[32:47]
	v_exp_f32_e32 v126, v126
	v_exp_f32_e32 v127, v127
	v_cvt_pk_bf16_f32 v234, v112, v113
	v_cvt_pk_bf16_f32 v235, v114, v115
	v_cvt_pk_bf16_f32 v236, v116, v117
	v_cvt_pk_bf16_f32 v237, v118, v119
	s_waitcnt lgkmcnt(2)
	v_mfma_f32_32x32x16_bf16 v[48:63], v[218:221], v[248:251], v[48:63]
	v_exp_f32_e32 v80, v80
	v_exp_f32_e32 v81, v81
	v_exp_f32_e32 v82, v82
	v_exp_f32_e32 v83, v83
	v_mfma_f32_32x32x16_bf16 v[0:15], v[222:225], v[184:187], v[0:15]
	ds_read_b64_tr_b16 v[184:185], v189 offset:28992
	ds_read_b64_tr_b16 v[186:187], v189 offset:30144
	v_exp_f32_e32 v84, v84
	v_exp_f32_e32 v85, v85
	v_exp_f32_e32 v86, v86
	v_exp_f32_e32 v87, v87
	v_mfma_f32_32x32x16_bf16 v[16:31], v[222:225], v[248:251], v[16:31]
	ds_read_b64_tr_b16 v[248:249], v189 offset:31232
	ds_read_b64_tr_b16 v[250:251], v189 offset:32384
	v_exp_f32_e32 v88, v88
	v_exp_f32_e32 v89, v89
	v_exp_f32_e32 v90, v90
	v_exp_f32_e32 v91, v91
	s_waitcnt lgkmcnt(4)
	v_mfma_f32_32x32x16_bf16 v[32:47], v[226:229], v[244:247], v[32:47]
	v_exp_f32_e32 v92, v92
	v_exp_f32_e32 v93, v93
	v_exp_f32_e32 v94, v94
	v_exp_f32_e32 v95, v95
	s_waitcnt lgkmcnt(2)
	v_mfma_f32_32x32x16_bf16 v[48:63], v[226:229], v[184:187], v[48:63]
	v_cvt_pk_bf16_f32 v176, v120, v121
	v_cvt_pk_bf16_f32 v177, v122, v123
	v_cvt_pk_bf16_f32 v178, v124, v125
	v_cvt_pk_bf16_f32 v179, v126, v127
	v_cvt_pk_bf16_f32 v238, v80, v81
	v_cvt_pk_bf16_f32 v239, v82, v83
	v_cvt_pk_bf16_f32 v240, v84, v85
	v_cvt_pk_bf16_f32 v241, v86, v87
	v_mfma_f32_32x32x16_bf16 v[0:15], v[230:233], v[244:247], v[0:15]
	ds_read_b64_tr_b16 v[244:245], v189 offset:31296
	ds_read_b64_tr_b16 v[246:247], v189 offset:32448
	v_cvt_pk_bf16_f32 v180, v88, v89
	v_cvt_pk_bf16_f32 v181, v90, v91
	v_cvt_pk_bf16_f32 v182, v92, v93
	v_cvt_pk_bf16_f32 v183, v94, v95
	v_add_f32_e32 v164, v96, v164
	v_add_f32_e32 v165, v64, v165
	v_add_f32_e32 v164, v97, v164
	v_mfma_f32_32x32x16_bf16 v[16:31], v[230:233], v[184:187], v[16:31]
	ds_read_b64_tr_b16 v[184:185], v189 offset:33536
	ds_read_b64_tr_b16 v[186:187], v189 offset:34688
	v_add_f32_e32 v165, v65, v165
	v_add_f32_e32 v164, v98, v164
	v_add_f32_e32 v165, v66, v165
	v_add_f32_e32 v164, v99, v164
	v_add_f32_e32 v165, v67, v165
	s_waitcnt lgkmcnt(4)
	v_mfma_f32_32x32x16_bf16 v[32:47], v[234:237], v[248:251], v[32:47]
	v_add_f32_e32 v164, v100, v164
	v_add_f32_e32 v165, v68, v165
	v_add_f32_e32 v164, v101, v164
	v_add_f32_e32 v165, v69, v165
	v_add_f32_e32 v164, v102, v164
	v_add_f32_e32 v165, v70, v165
	s_waitcnt lgkmcnt(2)
	v_mfma_f32_32x32x16_bf16 v[48:63], v[234:237], v[244:247], v[48:63]
	v_add_f32_e32 v164, v103, v164
	v_add_f32_e32 v165, v71, v165
	v_add_f32_e32 v164, v104, v164
	v_add_f32_e32 v165, v72, v165
	v_add_f32_e32 v164, v105, v164
	v_add_f32_e32 v165, v73, v165
	v_mfma_f32_32x32x16_bf16 v[0:15], v[238:241], v[248:251], v[0:15]
	ds_read_b64_tr_b16 v[248:249], v189 offset:33600
	ds_read_b64_tr_b16 v[250:251], v189 offset:34752
	v_add_f32_e32 v164, v106, v164
	v_add_f32_e32 v165, v74, v165
	v_add_f32_e32 v164, v107, v164
	v_add_f32_e32 v165, v75, v165
	v_add_f32_e32 v164, v108, v164
	v_mfma_f32_32x32x16_bf16 v[16:31], v[238:241], v[244:247], v[16:31]
	v_add_f32_e32 v165, v76, v165
	v_add_f32_e32 v164, v109, v164
	v_add_f32_e32 v165, v77, v165
	v_add_f32_e32 v164, v110, v164
	v_add_f32_e32 v165, v78, v165
	v_add_f32_e32 v164, v111, v164
	s_waitcnt lgkmcnt(2)
	v_mfma_f32_32x32x16_bf16 v[32:47], v[176:179], v[184:187], v[32:47]
	v_add_f32_e32 v165, v79, v165
	s_andn2_b64 vcc, exec, s[56:57]
	s_waitcnt lgkmcnt(0)
	v_mfma_f32_32x32x16_bf16 v[48:63], v[176:179], v[248:251], v[48:63]
	s_cbranch_vccnz .Lr2b_nowrite
	s_xor_b32 s58, s58, 1
	s_mul_i32 s34, s58, 0x3400
	v_add_u32_e32 v217, s34, v194
	s_waitcnt vmcnt(0)
	ds_write_b128 v217, v[152:155]
	s_and_saveexec_b64 s[56:57], s[40:41]
	s_cbranch_execz .Lr2b_nok2w
	v_add_u32_e32 v217, s34, v195
	ds_write_b128 v217, v[156:159]
.Lr2b_nok2w:
	s_or_b64 exec, exec, s[56:57]
	s_mulk_i32 s58, 0x2400
	v_add_u32_e32 v217, s58, v196
	ds_write_b128 v217, v[160:163] offset:26624
.Lr2b_nowrite:
	v_mfma_f32_32x32x16_bf16 v[0:15], v[180:183], v[184:187], v[0:15]
	v_mfma_f32_32x32x16_bf16 v[16:31], v[180:183], v[248:251], v[16:31]
	s_cmp_lg_u32 s28, s61
	s_mov_b32 s62, s61
	s_waitcnt lgkmcnt(0)
	s_barrier
	s_cbranch_scc1 .Lr2b_top
	v_add_f32_e32 v242, v112, v242
	v_add_f32_e32 v243, v80, v243
	v_add_f32_e32 v242, v113, v242
	v_add_f32_e32 v243, v81, v243
	v_add_f32_e32 v242, v114, v242
	v_add_f32_e32 v243, v82, v243
	v_add_f32_e32 v242, v115, v242
	v_add_f32_e32 v243, v83, v243
	v_add_f32_e32 v242, v116, v242
	v_add_f32_e32 v243, v84, v243
	v_add_f32_e32 v242, v117, v242
	v_add_f32_e32 v243, v85, v243
	v_add_f32_e32 v242, v118, v242
	v_add_f32_e32 v243, v86, v243
	v_add_f32_e32 v242, v119, v242
	v_add_f32_e32 v243, v87, v243
	v_add_f32_e32 v242, v120, v242
	v_add_f32_e32 v243, v88, v243
	v_add_f32_e32 v242, v121, v242
	v_add_f32_e32 v243, v89, v243
	v_add_f32_e32 v242, v122, v242
	v_add_f32_e32 v243, v90, v243
	v_add_f32_e32 v242, v123, v242
	v_add_f32_e32 v243, v91, v243
	v_add_f32_e32 v242, v124, v242
	v_add_f32_e32 v243, v92, v243
	v_add_f32_e32 v242, v125, v242
	v_add_f32_e32 v243, v93, v243
	v_add_f32_e32 v242, v126, v242
	v_add_f32_e32 v243, v94, v243
	v_add_f32_e32 v242, v127, v242
	v_add_f32_e32 v243, v95, v243
	v_add_f32_e32 v164, v164, v242
	v_add_f32_e32 v165, v165, v243
	v_mov_b32_e32 v244, v169
	v_mov_b32_e32 v245, v169
	v_mov_b32_e32 v246, v169
	v_mov_b32_e32 v247, v169

; __device__ __forceinline__ float rstd_from(const float* ps, int row, int off4, int n4, float inv_dim, int fq) {
;     float s = 0.f;
;     if (fq < n4) { const f32x4 v = *((const f32x4*)(ps + (size_t)row * 16) + off4 + fq); s = (v[0] + v[1]) + (v[2] + v[3]); }
;     s += __shfl_xor(s, 16); s += __shfl_xor(s, 32);
;     return rsqrtf(s * inv_dim + 1e-6f);
;     __device__ __forceinline__ void operator()(const f32x4 (&acc)[2][2][4][2], const Unit& u, int wr, int wc, int fr, int fq) const {
;         const int row0 = u.pm * BM + wr * 64 + fr, col0 = u.pn * 128 + wc * 32 + 8 * fq;
; #pragma unroll
;         for (int ai = 0; ai < 2; ++ai)
; #pragma unroll
;             for (int m = 0; m < 4; ++m) {
;                 const int row = row0 + ai * HALF + m * 16;
;                 const float rs = rstd_from(ps, row, 0, 4, 1.f / 1024.f, fq);
.LBB0_1171:
	v_and_b32_e32 v143, 64, v204
	v_xor_b32_e32 v141, 16, v204
	v_add_u32_e32 v143, 64, v143
	v_cmp_lt_i32_e32 vcc, v141, v143
	v_lshl_add_u32 v140, s7, 8, v145
	v_lshl_or_b32 v142, s2, 7, v147
	v_cndmask_b32_e32 v141, v204, v141, vcc
	v_lshlrev_b32_e32 v149, 2, v141
	v_xor_b32_e32 v141, 32, v204
	v_cmp_lt_i32_e32 vcc, v141, v143
	v_ashrrev_i32_e32 v143, 31, v142
	s_movk_i32 s4, 0x2000
	v_cndmask_b32_e32 v141, v204, v141, vcc
	v_lshlrev_b32_e32 v150, 2, v141
	v_ashrrev_i32_e32 v141, 31, v140
	v_lshlrev_b64 v[152:153], 6, v[140:141]
	s_mov_b32 s5, 0
	v_lshl_add_u64 v[152:153], v[134:135], 0, v[152:153]
	v_lshl_add_u64 v[154:155], v[152:153], 0, s[4:5]
	global_load_dwordx4 v[156:159], v[152:153], off
	global_load_dwordx4 v[160:163], v[152:153], off offset:1024
	global_load_dwordx4 v[164:167], v[152:153], off offset:2048
	global_load_dwordx4 v[172:175], v[152:153], off offset:3072
	global_load_dwordx4 v[176:179], v[154:155], off
	global_load_dwordx4 v[180:183], v[154:155], off offset:1024
	global_load_dwordx4 v[184:187], v[154:155], off offset:2048
	global_load_dwordx4 v[188:191], v[154:155], off offset:3072
	v_mov_b64_e32 v[236:237], s[26:27]
	v_lshlrev_b64 v[238:239], 1, v[142:143]
	v_mad_i64_i32 v[234:235], s[4:5], v140, s17, v[236:237]
	s_lshl_b32 s4, s17, 4
	s_mov_b32 s5, 0
	v_lshl_add_u64 v[234:235], v[234:235], 0, v[238:239]
	v_lshl_add_u64 v[236:237], s[4:5], 0, v[234:235]
	v_lshl_add_u64 v[238:239], s[4:5], 1, v[234:235]
	v_lshl_add_u64 v[240:241], s[4:5], 1, v[236:237]
	s_waitcnt vmcnt(7)
	v_add_f32_e32 v156, v157, v156
	v_add_f32_e32 v158, v158, v159
	s_waitcnt vmcnt(6)
	v_add_f32_e32 v160, v161, v160
	v_add_f32_e32 v162, v162, v163
	s_waitcnt vmcnt(5)
	v_add_f32_e32 v164, v165, v164
	v_add_f32_e32 v166, v166, v167
	s_waitcnt vmcnt(4)
	v_add_f32_e32 v172, v173, v172
	v_add_f32_e32 v174, v174, v175
	s_waitcnt vmcnt(3)
	v_add_f32_e32 v176, v177, v176
	v_add_f32_e32 v178, v178, v179
	s_waitcnt vmcnt(2)
	v_add_f32_e32 v180, v181, v180
	v_add_f32_e32 v182, v182, v183
	s_waitcnt vmcnt(1)
	v_add_f32_e32 v184, v185, v184
	v_add_f32_e32 v186, v186, v187
	s_waitcnt vmcnt(0)
	v_add_f32_e32 v188, v189, v188
	v_add_f32_e32 v190, v190, v191
	v_add_f32_e32 v156, v156, v158
	v_add_f32_e32 v160, v160, v162
	v_add_f32_e32 v164, v164, v166
	v_add_f32_e32 v172, v172, v174
	v_add_f32_e32 v176, v176, v178
	v_add_f32_e32 v180, v180, v182
	v_add_f32_e32 v184, v184, v186
	v_add_f32_e32 v188, v188, v190
	ds_bpermute_b32 v157, v149, v156
	ds_bpermute_b32 v161, v149, v160
	ds_bpermute_b32 v165, v149, v164
	ds_bpermute_b32 v173, v149, v172
	ds_bpermute_b32 v177, v149, v176
	ds_bpermute_b32 v181, v149, v180
	ds_bpermute_b32 v185, v149, v184
	ds_bpermute_b32 v189, v149, v188
	s_waitcnt lgkmcnt(7)
	v_add_f32_e32 v156, v156, v157
	s_waitcnt lgkmcnt(6)
	v_add_f32_e32 v160, v160, v161
	s_waitcnt lgkmcnt(5)
	v_add_f32_e32 v164, v164, v165
	s_waitcnt lgkmcnt(4)
	v_add_f32_e32 v172, v172, v173
	s_waitcnt lgkmcnt(3)
	v_add_f32_e32 v176, v176, v177
	s_waitcnt lgkmcnt(2)
	v_add_f32_e32 v180, v180, v181
	s_waitcnt lgkmcnt(1)
	v_add_f32_e32 v184, v184, v185
	s_waitcnt lgkmcnt(0)
	v_add_f32_e32 v188, v188, v189
	ds_bpermute_b32 v157, v150, v156
	ds_bpermute_b32 v161, v150, v160
	ds_bpermute_b32 v165, v150, v164
	ds_bpermute_b32 v173, v150, v172
	ds_bpermute_b32 v177, v150, v176
	ds_bpermute_b32 v181, v150, v180
	ds_bpermute_b32 v185, v150, v184
	ds_bpermute_b32 v189, v150, v188
	s_waitcnt lgkmcnt(7)
	v_add_f32_e32 v156, v156, v157
	s_waitcnt lgkmcnt(6)
	v_add_f32_e32 v160, v160, v161
	s_waitcnt lgkmcnt(5)
	v_add_f32_e32 v164, v164, v165
	s_waitcnt lgkmcnt(4)
	v_add_f32_e32 v172, v172, v173
	s_waitcnt lgkmcnt(3)
	v_add_f32_e32 v176, v176, v177
	s_waitcnt lgkmcnt(2)
	v_add_f32_e32 v180, v180, v181
	s_waitcnt lgkmcnt(1)
	v_add_f32_e32 v184, v184, v185
	s_waitcnt lgkmcnt(0)
	v_add_f32_e32 v188, v188, v189
	v_fmamk_f32 v156, v156, 0x3a800000, v202
	v_fmamk_f32 v160, v160, 0x3a800000, v202
	v_fmamk_f32 v164, v164, 0x3a800000, v202
	v_fmamk_f32 v172, v172, 0x3a800000, v202
	v_fmamk_f32 v176, v176, 0x3a800000, v202
	v_fmamk_f32 v180, v180, 0x3a800000, v202
	v_fmamk_f32 v184, v184, 0x3a800000, v202
	v_fmamk_f32 v188, v188, 0x3a800000, v202
	v_cmp_gt_f32_e32 vcc, s33, v156
	v_cmp_gt_f32_e64 s[4:5], s33, v160
	v_mul_f32_e32 v157, 0x4b800000, v156
	v_mul_f32_e32 v161, 0x4b800000, v160
	v_cndmask_b32_e32 v156, v156, v157, vcc
	v_cndmask_b32_e64 v160, v160, v161, s[4:5]
	v_rsq_f32_e32 v156, v156
	v_rsq_f32_e32 v160, v160
	v_mul_f32_e32 v157, 0x45800000, v156
	v_mul_f32_e32 v161, 0x45800000, v160
	v_cndmask_b32_e32 v158, v156, v157, vcc
	v_cndmask_b32_e64 v162, v160, v161, s[4:5]
	v_cmp_gt_f32_e32 vcc, s33, v164
	v_cmp_gt_f32_e64 s[4:5], s33, v172
	v_mul_f32_e32 v165, 0x4b800000, v164
	v_mul_f32_e32 v173, 0x4b800000, v172
	v_cndmask_b32_e32 v164, v164, v165, vcc
	v_cndmask_b32_e64 v172, v172, v173, s[4:5]
	v_rsq_f32_e32 v164, v164
	v_rsq_f32_e32 v172, v172
	v_mul_f32_e32 v165, 0x45800000, v164
	v_mul_f32_e32 v173, 0x45800000, v172
	v_cndmask_b32_e32 v166, v164, v165, vcc
	v_cndmask_b32_e64 v174, v172, v173, s[4:5]
	v_cmp_gt_f32_e32 vcc, s33, v176
	v_cmp_gt_f32_e64 s[4:5], s33, v180
	v_mul_f32_e32 v177, 0x4b800000, v176
	v_mul_f32_e32 v181, 0x4b800000, v180
	v_cndmask_b32_e32 v176, v176, v177, vcc
	v_cndmask_b32_e64 v180, v180, v181, s[4:5]
	v_rsq_f32_e32 v176, v176
	v_rsq_f32_e32 v180, v180
	v_mul_f32_e32 v177, 0x45800000, v176
	v_mul_f32_e32 v181, 0x45800000, v180
	v_cndmask_b32_e32 v178, v176, v177, vcc
	v_cndmask_b32_e64 v182, v180, v181, s[4:5]
	v_cmp_gt_f32_e32 vcc, s33, v184
	v_cmp_gt_f32_e64 s[4:5], s33, v188
	v_mul_f32_e32 v185, 0x4b800000, v184
	v_mul_f32_e32 v189, 0x4b800000, v188
; __device__ __forceinline__ unsigned cvt_pk_bf16(float lo, float hi) { unsigned r; asm volatile("v_cvt_pk_bf16_f32 %0, %1, %2" : "=v"(r) : "v"(lo), "v"(hi)); return r; }
;     __device__ __forceinline__ void operator()(const f32x4 (&acc)[2][2][4][2], const Unit& u, int wr, int wc, int fr, int fq) const {
;     ...
;                     for (int e = 0; e < 4; ++e) { const float gt = acc[ai][0][m][n][e] * rs, up = acc[ai][1][m][n][e] * rs;
;                         hv[n * 4 + e] = gt * __builtin_amdgcn_rcpf(1.f + __builtin_amdgcn_exp2f(-1.4426950408889634f * gt)) * up; }
;                 u32x4 w; w.x = cvt_pk_bf16(hv[0], hv[1]); w.y = cvt_pk_bf16(hv[2], hv[3]); w.z = cvt_pk_bf16(hv[4], hv[5]); w.w = cvt_pk_bf16(hv[6], hv[7]);
;                 *(u32x4*)(H + (size_t)row * 2816 + col0) = w;
	v_cndmask_b32_e32 v184, v184, v185, vcc
	v_cndmask_b32_e64 v188, v188, v189, s[4:5]
	v_rsq_f32_e32 v184, v184
	v_rsq_f32_e32 v188, v188
	v_mul_f32_e32 v185, 0x45800000, v184
	v_mul_f32_e32 v189, 0x45800000, v188
	v_cndmask_b32_e32 v186, v184, v185, vcc
	v_cndmask_b32_e64 v190, v188, v189, s[4:5]
	s_lshl_b32 s4, s17, 4
	s_mov_b32 s5, 0
	v_mul_f32_e32 v120, v120, v158
	v_mul_f32_e32 v121, v121, v158
	v_mul_f32_e32 v122, v122, v158
	v_mul_f32_e32 v123, v123, v158
	v_mul_f32_e32 v112, v112, v158
	v_mul_f32_e32 v113, v113, v158
	v_mul_f32_e32 v114, v114, v158
	v_mul_f32_e32 v115, v115, v158
	v_mul_f32_e32 v218, 0xbfb8aa3b, v120
	v_mul_f32_e32 v219, 0xbfb8aa3b, v121
	v_mul_f32_e32 v220, 0xbfb8aa3b, v122
	v_mul_f32_e32 v221, 0xbfb8aa3b, v123
	v_mul_f32_e32 v222, 0xbfb8aa3b, v112
	v_mul_f32_e32 v223, 0xbfb8aa3b, v113
	v_mul_f32_e32 v224, 0xbfb8aa3b, v114
	v_mul_f32_e32 v225, 0xbfb8aa3b, v115
	v_exp_f32_e32 v218, v218
	v_exp_f32_e32 v219, v219
	v_exp_f32_e32 v220, v220
	v_exp_f32_e32 v221, v221
	v_exp_f32_e32 v222, v222
	v_exp_f32_e32 v223, v223
	v_exp_f32_e32 v224, v224
	v_exp_f32_e32 v225, v225
	v_add_f32_e32 v218, 1.0, v218
	v_add_f32_e32 v219, 1.0, v219
	v_add_f32_e32 v220, 1.0, v220
	v_add_f32_e32 v221, 1.0, v221
	v_add_f32_e32 v222, 1.0, v222
	v_add_f32_e32 v223, 1.0, v223
	v_add_f32_e32 v224, 1.0, v224
	v_add_f32_e32 v225, 1.0, v225
	v_rcp_f32_e32 v218, v218
	v_rcp_f32_e32 v219, v219
	v_rcp_f32_e32 v220, v220
	v_rcp_f32_e32 v221, v221
	v_rcp_f32_e32 v222, v222
	v_rcp_f32_e32 v223, v223
	v_rcp_f32_e32 v224, v224
	v_rcp_f32_e32 v225, v225
	v_mul_f32_e32 v218, v120, v218
	v_mul_f32_e32 v219, v121, v219
	v_mul_f32_e32 v220, v122, v220
	v_mul_f32_e32 v221, v123, v221
	v_mul_f32_e32 v222, v112, v222
	v_mul_f32_e32 v223, v113, v223
	v_mul_f32_e32 v224, v114, v224
	v_mul_f32_e32 v225, v115, v225
	v_mul_f32_e32 v124, v124, v158
	v_mul_f32_e32 v125, v125, v158
	v_mul_f32_e32 v126, v126, v158
	v_mul_f32_e32 v127, v127, v158
	v_mul_f32_e32 v116, v116, v158
	v_mul_f32_e32 v117, v117, v158
	v_mul_f32_e32 v118, v118, v158
	v_mul_f32_e32 v119, v119, v158
	v_mul_f32_e32 v124, v124, v218
	v_mul_f32_e32 v125, v125, v219
	v_mul_f32_e32 v126, v126, v220
	v_mul_f32_e32 v127, v127, v221
	v_mul_f32_e32 v116, v116, v222
	v_mul_f32_e32 v117, v117, v223
	v_mul_f32_e32 v118, v118, v224
	v_mul_f32_e32 v119, v119, v225
	v_cvt_pk_bf16_f32 v226, v124, v125
	v_cvt_pk_bf16_f32 v227, v126, v127
	v_cvt_pk_bf16_f32 v228, v116, v117
	v_cvt_pk_bf16_f32 v229, v118, v119
	global_store_dwordx4 v[234:235], v[226:229], off
	v_mul_f32_e32 v104, v104, v162
	v_mul_f32_e32 v105, v105, v162
	v_mul_f32_e32 v106, v106, v162
	v_mul_f32_e32 v107, v107, v162
	v_mul_f32_e32 v96, v96, v162
	v_mul_f32_e32 v97, v97, v162
	v_mul_f32_e32 v98, v98, v162
	v_mul_f32_e32 v99, v99, v162
	v_mul_f32_e32 v218, 0xbfb8aa3b, v104
	v_mul_f32_e32 v219, 0xbfb8aa3b, v105
	v_mul_f32_e32 v220, 0xbfb8aa3b, v106
	v_mul_f32_e32 v221, 0xbfb8aa3b, v107
	v_mul_f32_e32 v222, 0xbfb8aa3b, v96
	v_mul_f32_e32 v223, 0xbfb8aa3b, v97
	v_mul_f32_e32 v224, 0xbfb8aa3b, v98
	v_mul_f32_e32 v225, 0xbfb8aa3b, v99
	v_exp_f32_e32 v218, v218
	v_exp_f32_e32 v219, v219
	v_exp_f32_e32 v220, v220
	v_exp_f32_e32 v221, v221
	v_exp_f32_e32 v222, v222
	v_exp_f32_e32 v223, v223
	v_exp_f32_e32 v224, v224
	v_exp_f32_e32 v225, v225
	v_add_f32_e32 v218, 1.0, v218
	v_add_f32_e32 v219, 1.0, v219
	v_add_f32_e32 v220, 1.0, v220
	v_add_f32_e32 v221, 1.0, v221
	v_add_f32_e32 v222, 1.0, v222
	v_add_f32_e32 v223, 1.0, v223
	v_add_f32_e32 v224, 1.0, v224
	v_add_f32_e32 v225, 1.0, v225
	v_rcp_f32_e32 v218, v218
	v_rcp_f32_e32 v219, v219
	v_rcp_f32_e32 v220, v220
	v_rcp_f32_e32 v221, v221
	v_rcp_f32_e32 v222, v222
	v_rcp_f32_e32 v223, v223
	v_rcp_f32_e32 v224, v224
	v_rcp_f32_e32 v225, v225
	v_mul_f32_e32 v218, v104, v218
	v_mul_f32_e32 v219, v105, v219
	v_mul_f32_e32 v220, v106, v220
	v_mul_f32_e32 v221, v107, v221
	v_mul_f32_e32 v222, v96, v222
	v_mul_f32_e32 v223, v97, v223
	v_mul_f32_e32 v224, v98, v224
	v_mul_f32_e32 v225, v99, v225
	v_mul_f32_e32 v108, v108, v162
	v_mul_f32_e32 v109, v109, v162
	v_mul_f32_e32 v110, v110, v162
	v_mul_f32_e32 v111, v111, v162
	v_mul_f32_e32 v100, v100, v162
	v_mul_f32_e32 v101, v101, v162
	v_mul_f32_e32 v102, v102, v162
	v_mul_f32_e32 v103, v103, v162
	v_mul_f32_e32 v108, v108, v218
	v_mul_f32_e32 v109, v109, v219
	v_mul_f32_e32 v110, v110, v220
	v_mul_f32_e32 v111, v111, v221
	v_mul_f32_e32 v100, v100, v222
	v_mul_f32_e32 v101, v101, v223
	v_mul_f32_e32 v102, v102, v224
	v_mul_f32_e32 v103, v103, v225
	v_cvt_pk_bf16_f32 v230, v108, v109
	v_cvt_pk_bf16_f32 v231, v110, v111
	v_cvt_pk_bf16_f32 v232, v100, v101
	v_cvt_pk_bf16_f32 v233, v102, v103
	global_store_dwordx4 v[236:237], v[230:233], off
	v_mul_f32_e32 v88, v88, v166
	v_mul_f32_e32 v89, v89, v166
	v_mul_f32_e32 v90, v90, v166
	v_mul_f32_e32 v91, v91, v166
	v_mul_f32_e32 v80, v80, v166
	v_mul_f32_e32 v81, v81, v166
	v_mul_f32_e32 v82, v82, v166
	v_mul_f32_e32 v83, v83, v166
	v_mul_f32_e32 v218, 0xbfb8aa3b, v88
	v_mul_f32_e32 v219, 0xbfb8aa3b, v89
	v_mul_f32_e32 v220, 0xbfb8aa3b, v90
	v_mul_f32_e32 v221, 0xbfb8aa3b, v91
	v_mul_f32_e32 v222, 0xbfb8aa3b, v80
	v_mul_f32_e32 v223, 0xbfb8aa3b, v81
	v_mul_f32_e32 v224, 0xbfb8aa3b, v82
	v_mul_f32_e32 v225, 0xbfb8aa3b, v83
	v_exp_f32_e32 v218, v218
	v_exp_f32_e32 v219, v219
	v_exp_f32_e32 v220, v220
	v_exp_f32_e32 v221, v221
	v_exp_f32_e32 v222, v222
	v_exp_f32_e32 v223, v223
	v_exp_f32_e32 v224, v224
	v_exp_f32_e32 v225, v225
	v_add_f32_e32 v218, 1.0, v218
	v_add_f32_e32 v219, 1.0, v219
	v_add_f32_e32 v220, 1.0, v220
	v_add_f32_e32 v221, 1.0, v221
	v_add_f32_e32 v222, 1.0, v222
	v_add_f32_e32 v223, 1.0, v223
	v_add_f32_e32 v224, 1.0, v224
; __device__ __forceinline__ unsigned cvt_pk_bf16(float lo, float hi) { unsigned r; asm volatile("v_cvt_pk_bf16_f32 %0, %1, %2" : "=v"(r) : "v"(lo), "v"(hi)); return r; }
;     __device__ __forceinline__ void operator()(const f32x4 (&acc)[2][2][4][2], const Unit& u, int wr, int wc, int fr, int fq) const {
;     ...
;                     for (int e = 0; e < 4; ++e) { const float gt = acc[ai][0][m][n][e] * rs, up = acc[ai][1][m][n][e] * rs;
;                         hv[n * 4 + e] = gt * __builtin_amdgcn_rcpf(1.f + __builtin_amdgcn_exp2f(-1.4426950408889634f * gt)) * up; }
;                 u32x4 w; w.x = cvt_pk_bf16(hv[0], hv[1]); w.y = cvt_pk_bf16(hv[2], hv[3]); w.z = cvt_pk_bf16(hv[4], hv[5]); w.w = cvt_pk_bf16(hv[6], hv[7]);
;                 *(u32x4*)(H + (size_t)row * 2816 + col0) = w;
	v_add_f32_e32 v225, 1.0, v225
	v_rcp_f32_e32 v218, v218
	v_rcp_f32_e32 v219, v219
	v_rcp_f32_e32 v220, v220
	v_rcp_f32_e32 v221, v221
	v_rcp_f32_e32 v222, v222
	v_rcp_f32_e32 v223, v223
	v_rcp_f32_e32 v224, v224
	v_rcp_f32_e32 v225, v225
	v_mul_f32_e32 v218, v88, v218
	v_mul_f32_e32 v219, v89, v219
	v_mul_f32_e32 v220, v90, v220
	v_mul_f32_e32 v221, v91, v221
	v_mul_f32_e32 v222, v80, v222
	v_mul_f32_e32 v223, v81, v223
	v_mul_f32_e32 v224, v82, v224
	v_mul_f32_e32 v225, v83, v225
	v_mul_f32_e32 v92, v92, v166
	v_mul_f32_e32 v93, v93, v166
	v_mul_f32_e32 v94, v94, v166
	v_mul_f32_e32 v95, v95, v166
	v_mul_f32_e32 v84, v84, v166
	v_mul_f32_e32 v85, v85, v166
	v_mul_f32_e32 v86, v86, v166
	v_mul_f32_e32 v87, v87, v166
	v_mul_f32_e32 v92, v92, v218
	v_mul_f32_e32 v93, v93, v219
	v_mul_f32_e32 v94, v94, v220
	v_mul_f32_e32 v95, v95, v221
	v_mul_f32_e32 v84, v84, v222
	v_mul_f32_e32 v85, v85, v223
	v_mul_f32_e32 v86, v86, v224
	v_mul_f32_e32 v87, v87, v225
	v_cvt_pk_bf16_f32 v226, v92, v93
	v_cvt_pk_bf16_f32 v227, v94, v95
	v_cvt_pk_bf16_f32 v228, v84, v85
	v_cvt_pk_bf16_f32 v229, v86, v87
	global_store_dwordx4 v[238:239], v[226:229], off
	v_mul_f32_e32 v72, v72, v174
	v_mul_f32_e32 v73, v73, v174
	v_mul_f32_e32 v74, v74, v174
	v_mul_f32_e32 v75, v75, v174
	v_mul_f32_e32 v64, v64, v174
	v_mul_f32_e32 v65, v65, v174
	v_mul_f32_e32 v66, v66, v174
	v_mul_f32_e32 v67, v67, v174
	v_mul_f32_e32 v218, 0xbfb8aa3b, v72
	v_mul_f32_e32 v219, 0xbfb8aa3b, v73
	v_mul_f32_e32 v220, 0xbfb8aa3b, v74
	v_mul_f32_e32 v221, 0xbfb8aa3b, v75
	v_mul_f32_e32 v222, 0xbfb8aa3b, v64
	v_mul_f32_e32 v223, 0xbfb8aa3b, v65
	v_mul_f32_e32 v224, 0xbfb8aa3b, v66
	v_mul_f32_e32 v225, 0xbfb8aa3b, v67
	v_exp_f32_e32 v218, v218
	v_exp_f32_e32 v219, v219
	v_exp_f32_e32 v220, v220
	v_exp_f32_e32 v221, v221
	v_exp_f32_e32 v222, v222
	v_exp_f32_e32 v223, v223
	v_exp_f32_e32 v224, v224
	v_exp_f32_e32 v225, v225
	v_add_f32_e32 v218, 1.0, v218
	v_add_f32_e32 v219, 1.0, v219
	v_add_f32_e32 v220, 1.0, v220
	v_add_f32_e32 v221, 1.0, v221
	v_add_f32_e32 v222, 1.0, v222
	v_add_f32_e32 v223, 1.0, v223
	v_add_f32_e32 v224, 1.0, v224
	v_add_f32_e32 v225, 1.0, v225
	v_rcp_f32_e32 v218, v218
	v_rcp_f32_e32 v219, v219
	v_rcp_f32_e32 v220, v220
	v_rcp_f32_e32 v221, v221
	v_rcp_f32_e32 v222, v222
	v_rcp_f32_e32 v223, v223
	v_rcp_f32_e32 v224, v224
	v_rcp_f32_e32 v225, v225
	v_mul_f32_e32 v218, v72, v218
	v_mul_f32_e32 v219, v73, v219
	v_mul_f32_e32 v220, v74, v220
	v_mul_f32_e32 v221, v75, v221
	v_mul_f32_e32 v222, v64, v222
	v_mul_f32_e32 v223, v65, v223
	v_mul_f32_e32 v224, v66, v224
	v_mul_f32_e32 v225, v67, v225
	v_mul_f32_e32 v76, v76, v174
	v_mul_f32_e32 v77, v77, v174
	v_mul_f32_e32 v78, v78, v174
	v_mul_f32_e32 v79, v79, v174
	v_mul_f32_e32 v68, v68, v174
	v_mul_f32_e32 v69, v69, v174
	v_mul_f32_e32 v70, v70, v174
	v_mul_f32_e32 v71, v71, v174
	v_mul_f32_e32 v76, v76, v218
	v_mul_f32_e32 v77, v77, v219
	v_mul_f32_e32 v78, v78, v220
	v_mul_f32_e32 v79, v79, v221
	v_mul_f32_e32 v68, v68, v222
	v_mul_f32_e32 v69, v69, v223
	v_mul_f32_e32 v70, v70, v224
	v_mul_f32_e32 v71, v71, v225
	v_cvt_pk_bf16_f32 v230, v76, v77
	v_cvt_pk_bf16_f32 v231, v78, v79
	v_cvt_pk_bf16_f32 v232, v68, v69
	v_cvt_pk_bf16_f32 v233, v70, v71
	global_store_dwordx4 v[240:241], v[230:233], off
	v_mul_f32_e32 v56, v56, v178
	v_mul_f32_e32 v57, v57, v178
	v_mul_f32_e32 v58, v58, v178
	v_mul_f32_e32 v59, v59, v178
	v_mul_f32_e32 v48, v48, v178
	v_mul_f32_e32 v49, v49, v178
	v_mul_f32_e32 v50, v50, v178
	v_mul_f32_e32 v51, v51, v178
	v_mul_f32_e32 v218, 0xbfb8aa3b, v56
	v_mul_f32_e32 v219, 0xbfb8aa3b, v57
	v_mul_f32_e32 v220, 0xbfb8aa3b, v58
	v_mul_f32_e32 v221, 0xbfb8aa3b, v59
	v_mul_f32_e32 v222, 0xbfb8aa3b, v48
	v_mul_f32_e32 v223, 0xbfb8aa3b, v49
	v_mul_f32_e32 v224, 0xbfb8aa3b, v50
	v_mul_f32_e32 v225, 0xbfb8aa3b, v51
	v_exp_f32_e32 v218, v218
	v_exp_f32_e32 v219, v219
	v_exp_f32_e32 v220, v220
	v_exp_f32_e32 v221, v221
	v_exp_f32_e32 v222, v222
	v_exp_f32_e32 v223, v223
	v_exp_f32_e32 v224, v224
	v_exp_f32_e32 v225, v225
	v_add_f32_e32 v218, 1.0, v218
	v_add_f32_e32 v219, 1.0, v219
	v_add_f32_e32 v220, 1.0, v220
	v_add_f32_e32 v221, 1.0, v221
	v_add_f32_e32 v222, 1.0, v222
	v_add_f32_e32 v223, 1.0, v223
	v_add_f32_e32 v224, 1.0, v224
	v_add_f32_e32 v225, 1.0, v225
	v_rcp_f32_e32 v218, v218
	v_rcp_f32_e32 v219, v219
	v_rcp_f32_e32 v220, v220
	v_rcp_f32_e32 v221, v221
	v_rcp_f32_e32 v222, v222
	v_rcp_f32_e32 v223, v223
	v_rcp_f32_e32 v224, v224
	v_rcp_f32_e32 v225, v225
	v_mul_f32_e32 v218, v56, v218
	v_mul_f32_e32 v219, v57, v219
	v_mul_f32_e32 v220, v58, v220
	v_mul_f32_e32 v221, v59, v221
	v_mul_f32_e32 v222, v48, v222
	v_mul_f32_e32 v223, v49, v223
	v_mul_f32_e32 v224, v50, v224
	v_mul_f32_e32 v225, v51, v225
	v_mul_f32_e32 v60, v60, v178
	v_mul_f32_e32 v61, v61, v178
	v_mul_f32_e32 v62, v62, v178
	v_mul_f32_e32 v63, v63, v178
	v_mul_f32_e32 v52, v52, v178
	v_mul_f32_e32 v53, v53, v178
	v_mul_f32_e32 v54, v54, v178
	v_mul_f32_e32 v55, v55, v178
	v_mul_f32_e32 v60, v60, v218
	v_mul_f32_e32 v61, v61, v219
	v_mul_f32_e32 v62, v62, v220
	v_mul_f32_e32 v63, v63, v221
	v_mul_f32_e32 v52, v52, v222
	v_mul_f32_e32 v53, v53, v223
	v_mul_f32_e32 v54, v54, v224
	v_mul_f32_e32 v55, v55, v225
	v_cvt_pk_bf16_f32 v226, v60, v61
	v_cvt_pk_bf16_f32 v227, v62, v63
	v_cvt_pk_bf16_f32 v228, v52, v53
	v_cvt_pk_bf16_f32 v229, v54, v55
	v_lshl_add_u64 v[242:243], s[4:5], 3, v[234:235]
	global_store_dwordx4 v[242:243], v[226:229], off
	v_mul_f32_e32 v40, v40, v182
	v_mul_f32_e32 v41, v41, v182
	v_mul_f32_e32 v42, v42, v182
	v_mul_f32_e32 v43, v43, v182
	v_mul_f32_e32 v32, v32, v182
	v_mul_f32_e32 v33, v33, v182
	v_mul_f32_e32 v34, v34, v182
; __device__ __forceinline__ unsigned cvt_pk_bf16(float lo, float hi) { unsigned r; asm volatile("v_cvt_pk_bf16_f32 %0, %1, %2" : "=v"(r) : "v"(lo), "v"(hi)); return r; }
;     __device__ __forceinline__ void operator()(const f32x4 (&acc)[2][2][4][2], const Unit& u, int wr, int wc, int fr, int fq) const {
;     ...
;         for (int ai = 0; ai < 2; ++ai)
; #pragma unroll
;             for (int m = 0; m < 4; ++m) {
;                 const int row = row0 + ai * HALF + m * 16;
;                 const float rs = rstd_from(ps, row, 0, 4, 1.f / 1024.f, fq);
;                 float hv[8];
; #pragma unroll
;                 for (int n = 0; n < 2; ++n)
; #pragma unroll
;                     for (int e = 0; e < 4; ++e) { const float gt = acc[ai][0][m][n][e] * rs, up = acc[ai][1][m][n][e] * rs;
;                         hv[n * 4 + e] = gt * __builtin_amdgcn_rcpf(1.f + __builtin_amdgcn_exp2f(-1.4426950408889634f * gt)) * up; }
;                 u32x4 w; w.x = cvt_pk_bf16(hv[0], hv[1]); w.y = cvt_pk_bf16(hv[2], hv[3]); w.z = cvt_pk_bf16(hv[4], hv[5]); w.w = cvt_pk_bf16(hv[6], hv[7]);
;                 *(u32x4*)(H + (size_t)row * 2816 + col0) = w;
;             }
; template <class Epi, class Sched, bool ALIGN_EPI = false, bool SP2 = false>
; __device__ __forceinline__ void gemm_phase(PG8_LAS unsigned char* lds, const Gemm g, const Sched& S, const Epi& E) {
;     ...
;         if constexpr (!Epi::AFTER_DRAIN) { E(acc, cur, wr, wc, fr, fq); S.done(cur); }
;         if (!has_next) break;
	v_mul_f32_e32 v35, v35, v182
	v_mul_f32_e32 v218, 0xbfb8aa3b, v40
	v_mul_f32_e32 v219, 0xbfb8aa3b, v41
	v_mul_f32_e32 v220, 0xbfb8aa3b, v42
	v_mul_f32_e32 v221, 0xbfb8aa3b, v43
	v_mul_f32_e32 v222, 0xbfb8aa3b, v32
	v_mul_f32_e32 v223, 0xbfb8aa3b, v33
	v_mul_f32_e32 v224, 0xbfb8aa3b, v34
	v_mul_f32_e32 v225, 0xbfb8aa3b, v35
	v_exp_f32_e32 v218, v218
	v_exp_f32_e32 v219, v219
	v_exp_f32_e32 v220, v220
	v_exp_f32_e32 v221, v221
	v_exp_f32_e32 v222, v222
	v_exp_f32_e32 v223, v223
	v_exp_f32_e32 v224, v224
	v_exp_f32_e32 v225, v225
	v_add_f32_e32 v218, 1.0, v218
	v_add_f32_e32 v219, 1.0, v219
	v_add_f32_e32 v220, 1.0, v220
	v_add_f32_e32 v221, 1.0, v221
	v_add_f32_e32 v222, 1.0, v222
	v_add_f32_e32 v223, 1.0, v223
	v_add_f32_e32 v224, 1.0, v224
	v_add_f32_e32 v225, 1.0, v225
	v_rcp_f32_e32 v218, v218
	v_rcp_f32_e32 v219, v219
	v_rcp_f32_e32 v220, v220
	v_rcp_f32_e32 v221, v221
	v_rcp_f32_e32 v222, v222
	v_rcp_f32_e32 v223, v223
	v_rcp_f32_e32 v224, v224
	v_rcp_f32_e32 v225, v225
	v_mul_f32_e32 v218, v40, v218
	v_mul_f32_e32 v219, v41, v219
	v_mul_f32_e32 v220, v42, v220
	v_mul_f32_e32 v221, v43, v221
	v_mul_f32_e32 v222, v32, v222
	v_mul_f32_e32 v223, v33, v223
	v_mul_f32_e32 v224, v34, v224
	v_mul_f32_e32 v225, v35, v225
	v_mul_f32_e32 v44, v44, v182
	v_mul_f32_e32 v45, v45, v182
	v_mul_f32_e32 v46, v46, v182
	v_mul_f32_e32 v47, v47, v182
	v_mul_f32_e32 v36, v36, v182
	v_mul_f32_e32 v37, v37, v182
	v_mul_f32_e32 v38, v38, v182
	v_mul_f32_e32 v39, v39, v182
	v_mul_f32_e32 v44, v44, v218
	v_mul_f32_e32 v45, v45, v219
	v_mul_f32_e32 v46, v46, v220
	v_mul_f32_e32 v47, v47, v221
	v_mul_f32_e32 v36, v36, v222
	v_mul_f32_e32 v37, v37, v223
	v_mul_f32_e32 v38, v38, v224
	v_mul_f32_e32 v39, v39, v225
	v_cvt_pk_bf16_f32 v230, v44, v45
	v_cvt_pk_bf16_f32 v231, v46, v47
	v_cvt_pk_bf16_f32 v232, v36, v37
	v_cvt_pk_bf16_f32 v233, v38, v39
	v_lshl_add_u64 v[242:243], s[4:5], 3, v[236:237]
	global_store_dwordx4 v[242:243], v[230:233], off
	v_mul_f32_e32 v24, v24, v186
	v_mul_f32_e32 v25, v25, v186
	v_mul_f32_e32 v26, v26, v186
	v_mul_f32_e32 v27, v27, v186
	v_mul_f32_e32 v16, v16, v186
	v_mul_f32_e32 v17, v17, v186
	v_mul_f32_e32 v18, v18, v186
	v_mul_f32_e32 v19, v19, v186
	v_mul_f32_e32 v218, 0xbfb8aa3b, v24
	v_mul_f32_e32 v219, 0xbfb8aa3b, v25
	v_mul_f32_e32 v220, 0xbfb8aa3b, v26
	v_mul_f32_e32 v221, 0xbfb8aa3b, v27
	v_mul_f32_e32 v222, 0xbfb8aa3b, v16
	v_mul_f32_e32 v223, 0xbfb8aa3b, v17
	v_mul_f32_e32 v224, 0xbfb8aa3b, v18
	v_mul_f32_e32 v225, 0xbfb8aa3b, v19
	v_exp_f32_e32 v218, v218
	v_exp_f32_e32 v219, v219
	v_exp_f32_e32 v220, v220
	v_exp_f32_e32 v221, v221
	v_exp_f32_e32 v222, v222
	v_exp_f32_e32 v223, v223
	v_exp_f32_e32 v224, v224
	v_exp_f32_e32 v225, v225
	v_add_f32_e32 v218, 1.0, v218
	v_add_f32_e32 v219, 1.0, v219
	v_add_f32_e32 v220, 1.0, v220
	v_add_f32_e32 v221, 1.0, v221
	v_add_f32_e32 v222, 1.0, v222
	v_add_f32_e32 v223, 1.0, v223
	v_add_f32_e32 v224, 1.0, v224
	v_add_f32_e32 v225, 1.0, v225
	v_rcp_f32_e32 v218, v218
	v_rcp_f32_e32 v219, v219
	v_rcp_f32_e32 v220, v220
	v_rcp_f32_e32 v221, v221
	v_rcp_f32_e32 v222, v222
	v_rcp_f32_e32 v223, v223
	v_rcp_f32_e32 v224, v224
	v_rcp_f32_e32 v225, v225
	v_mul_f32_e32 v218, v24, v218
	v_mul_f32_e32 v219, v25, v219
	v_mul_f32_e32 v220, v26, v220
	v_mul_f32_e32 v221, v27, v221
	v_mul_f32_e32 v222, v16, v222
	v_mul_f32_e32 v223, v17, v223
	v_mul_f32_e32 v224, v18, v224
	v_mul_f32_e32 v225, v19, v225
	v_mul_f32_e32 v28, v28, v186
	v_mul_f32_e32 v29, v29, v186
	v_mul_f32_e32 v30, v30, v186
	v_mul_f32_e32 v31, v31, v186
	v_mul_f32_e32 v20, v20, v186
	v_mul_f32_e32 v21, v21, v186
	v_mul_f32_e32 v22, v22, v186
	v_mul_f32_e32 v23, v23, v186
	v_mul_f32_e32 v28, v28, v218
	v_mul_f32_e32 v29, v29, v219
	v_mul_f32_e32 v30, v30, v220
	v_mul_f32_e32 v31, v31, v221
	v_mul_f32_e32 v20, v20, v222
	v_mul_f32_e32 v21, v21, v223
	v_mul_f32_e32 v22, v22, v224
	v_mul_f32_e32 v23, v23, v225
	v_cvt_pk_bf16_f32 v226, v28, v29
	v_cvt_pk_bf16_f32 v227, v30, v31
	v_cvt_pk_bf16_f32 v228, v20, v21
	v_cvt_pk_bf16_f32 v229, v22, v23
	v_lshl_add_u64 v[242:243], s[4:5], 3, v[238:239]
	global_store_dwordx4 v[242:243], v[226:229], off
	v_mul_f32_e32 v8, v8, v190
	v_mul_f32_e32 v9, v9, v190
	v_mul_f32_e32 v10, v10, v190
	v_mul_f32_e32 v11, v11, v190
	v_mul_f32_e32 v4, v4, v190
	v_mul_f32_e32 v5, v5, v190
	v_mul_f32_e32 v6, v6, v190
	v_mul_f32_e32 v7, v7, v190
	v_mul_f32_e32 v218, 0xbfb8aa3b, v8
	v_mul_f32_e32 v219, 0xbfb8aa3b, v9
	v_mul_f32_e32 v220, 0xbfb8aa3b, v10
	v_mul_f32_e32 v221, 0xbfb8aa3b, v11
	v_mul_f32_e32 v222, 0xbfb8aa3b, v4
	v_mul_f32_e32 v223, 0xbfb8aa3b, v5
	v_mul_f32_e32 v224, 0xbfb8aa3b, v6
	v_mul_f32_e32 v225, 0xbfb8aa3b, v7
	v_exp_f32_e32 v218, v218
	v_exp_f32_e32 v219, v219
	v_exp_f32_e32 v220, v220
	v_exp_f32_e32 v221, v221
	v_exp_f32_e32 v222, v222
	v_exp_f32_e32 v223, v223
	v_exp_f32_e32 v224, v224
	v_exp_f32_e32 v225, v225
	v_add_f32_e32 v218, 1.0, v218
	v_add_f32_e32 v219, 1.0, v219
	v_add_f32_e32 v220, 1.0, v220
	v_add_f32_e32 v221, 1.0, v221
	v_add_f32_e32 v222, 1.0, v222
	v_add_f32_e32 v223, 1.0, v223
	v_add_f32_e32 v224, 1.0, v224
	v_add_f32_e32 v225, 1.0, v225
	v_rcp_f32_e32 v218, v218
	v_rcp_f32_e32 v219, v219
	v_rcp_f32_e32 v220, v220
	v_rcp_f32_e32 v221, v221
	v_rcp_f32_e32 v222, v222
	v_rcp_f32_e32 v223, v223
	v_rcp_f32_e32 v224, v224
	v_rcp_f32_e32 v225, v225
	v_mul_f32_e32 v218, v8, v218
	v_mul_f32_e32 v219, v9, v219
	v_mul_f32_e32 v220, v10, v220
	v_mul_f32_e32 v221, v11, v221
	v_mul_f32_e32 v222, v4, v222
	v_mul_f32_e32 v223, v5, v223
	v_mul_f32_e32 v224, v6, v224
	v_mul_f32_e32 v225, v7, v225
	v_mul_f32_e32 v12, v12, v190
	v_mul_f32_e32 v13, v13, v190
	v_mul_f32_e32 v14, v14, v190
	v_mul_f32_e32 v15, v15, v190
	v_mul_f32_e32 v0, v0, v190
	v_mul_f32_e32 v1, v1, v190
	v_mul_f32_e32 v2, v2, v190
	v_mul_f32_e32 v3, v3, v190
	v_mul_f32_e32 v12, v12, v218
	v_mul_f32_e32 v13, v13, v219
	v_mul_f32_e32 v14, v14, v220
	v_mul_f32_e32 v15, v15, v221
	v_mul_f32_e32 v0, v0, v222
	v_mul_f32_e32 v1, v1, v223
	v_mul_f32_e32 v2, v2, v224
	v_mul_f32_e32 v3, v3, v225
	v_cvt_pk_bf16_f32 v230, v12, v13
	v_cvt_pk_bf16_f32 v231, v14, v15
	v_cvt_pk_bf16_f32 v232, v0, v1
	v_cvt_pk_bf16_f32 v233, v2, v3
	v_lshl_add_u64 v[242:243], s[4:5], 3, v[240:241]
	global_store_dwordx4 v[242:243], v[230:233], off
	s_and_b64 vcc, exec, s[38:39]
	s_mov_b64 s[4:5], -1
	s_cbranch_vccnz .LBB0_1159
	s_andn2_b64 vcc, exec, s[44:45]
	s_cbranch_vccnz .LBB0_1158
	s_barrier
	s_branch .LBB0_1158
